# v4 + attention output epilogue: 16 dwordx2 stores per lane widened to 8 dwordx4 via v_permlane32_swap pairs
# speedup vs baseline: 1.0250x; 1.0060x over previous
.LBB0_1509:
	v_mov_b32_e32 v64, v181
	s_nop 1
	v_permlane32_swap_b32_e32 v181, v64
	v_add_f32_e32 v64, v181, v64
	v_div_scale_f32 v65, s[14:15], v64, v64, 1.0
	v_rcp_f32_e32 v66, v65
	s_add_i32 s61, s61, s62
	s_mul_i32 s14, s60, 0xc0
	s_ashr_i32 s15, s14, 31
	v_fma_f32 v67, -v65, v66, 1.0
	v_fmac_f32_e32 v66, v67, v66
	v_div_scale_f32 v67, vcc, 1.0, v64, 1.0
	v_mul_f32_e32 v68, v67, v66
	v_fma_f32 v69, -v65, v68, v67
	v_fmac_f32_e32 v68, v69, v66
	v_fma_f32 v65, -v65, v68, v67
	v_div_fmas_f32 v65, v65, v66, v68
	v_div_fixup_f32 v64, v65, v64, 1.0
	v_or_b32_e32 v65, s61, v171
	v_mov_b64_e32 v[66:67], s[4:5]
	v_mad_i64_i32 v[66:67], s[16:17], v65, s58, v[66:67]
	v_lshl_add_u64 v[66:67], s[14:15], 1, v[66:67]
	v_lshlrev_b32_e32 v164, 1, v173
	v_lshl_add_u64 v[66:67], v[66:67], 0, v[164:165]
	v_lshl_add_u64 v[66:67], v[66:67], 0, v[164:165]
	v_pk_mul_f32 v[48:49], v[48:49], v[64:65] op_sel_hi:[1,0]
	v_pk_mul_f32 v[50:51], v[50:51], v[64:65] op_sel_hi:[1,0]
	v_pk_mul_f32 v[52:53], v[52:53], v[64:65] op_sel_hi:[1,0]
	v_pk_mul_f32 v[54:55], v[54:55], v[64:65] op_sel_hi:[1,0]
	v_pk_mul_f32 v[32:33], v[32:33], v[64:65] op_sel_hi:[1,0]
	v_pk_mul_f32 v[34:35], v[34:35], v[64:65] op_sel_hi:[1,0]
	v_pk_mul_f32 v[36:37], v[36:37], v[64:65] op_sel_hi:[1,0]
	v_pk_mul_f32 v[38:39], v[38:39], v[64:65] op_sel_hi:[1,0]
	v_pk_mul_f32 v[16:17], v[16:17], v[64:65] op_sel_hi:[1,0]
	v_pk_mul_f32 v[18:19], v[18:19], v[64:65] op_sel_hi:[1,0]
	v_pk_mul_f32 v[20:21], v[20:21], v[64:65] op_sel_hi:[1,0]
	v_pk_mul_f32 v[22:23], v[22:23], v[64:65] op_sel_hi:[1,0]
	v_pk_mul_f32 v[0:1], v[0:1], v[64:65] op_sel_hi:[1,0]
	v_pk_mul_f32 v[2:3], v[2:3], v[64:65] op_sel_hi:[1,0]
	v_pk_mul_f32 v[4:5], v[4:5], v[64:65] op_sel_hi:[1,0]
	v_pk_mul_f32 v[6:7], v[6:7], v[64:65] op_sel_hi:[1,0]
	v_cvt_pk_bf16_f32 v48, v48, v49
	v_cvt_pk_bf16_f32 v49, v50, v51
	v_cvt_pk_bf16_f32 v50, v52, v53
	v_cvt_pk_bf16_f32 v51, v54, v55
	v_cvt_pk_bf16_f32 v32, v32, v33
	v_cvt_pk_bf16_f32 v33, v34, v35
	v_cvt_pk_bf16_f32 v34, v36, v37
	v_cvt_pk_bf16_f32 v35, v38, v39
	v_cvt_pk_bf16_f32 v16, v16, v17
	v_cvt_pk_bf16_f32 v17, v18, v19
	v_cvt_pk_bf16_f32 v18, v20, v21
	v_cvt_pk_bf16_f32 v19, v22, v23
	v_cvt_pk_bf16_f32 v0, v0, v1
	v_cvt_pk_bf16_f32 v1, v2, v3
	v_cvt_pk_bf16_f32 v2, v4, v5
	v_cvt_pk_bf16_f32 v3, v6, v7
	v_permlane32_swap_b32_e32 v48, v50
	v_permlane32_swap_b32_e32 v49, v51
	v_permlane32_swap_b32_e32 v32, v34
	v_permlane32_swap_b32_e32 v33, v35
	v_permlane32_swap_b32_e32 v16, v18
	v_permlane32_swap_b32_e32 v17, v19
	v_permlane32_swap_b32_e32 v0, v2
	v_permlane32_swap_b32_e32 v1, v3
	global_store_dwordx4 v[66:67], v[48:51], off
	global_store_dwordx4 v[66:67], v[32:35], off offset:64
	global_store_dwordx4 v[66:67], v[16:19], off offset:128
	global_store_dwordx4 v[66:67], v[0:3], off offset:192
	v_pk_mul_f32 v[56:57], v[56:57], v[64:65] op_sel_hi:[1,0]
	v_pk_mul_f32 v[58:59], v[58:59], v[64:65] op_sel_hi:[1,0]
	v_pk_mul_f32 v[60:61], v[60:61], v[64:65] op_sel_hi:[1,0]
	v_pk_mul_f32 v[62:63], v[62:63], v[64:65] op_sel_hi:[1,0]
	v_pk_mul_f32 v[40:41], v[40:41], v[64:65] op_sel_hi:[1,0]
	v_pk_mul_f32 v[42:43], v[42:43], v[64:65] op_sel_hi:[1,0]
	v_pk_mul_f32 v[44:45], v[44:45], v[64:65] op_sel_hi:[1,0]
	v_pk_mul_f32 v[46:47], v[46:47], v[64:65] op_sel_hi:[1,0]
	v_pk_mul_f32 v[24:25], v[24:25], v[64:65] op_sel_hi:[1,0]
	v_pk_mul_f32 v[26:27], v[26:27], v[64:65] op_sel_hi:[1,0]
	v_pk_mul_f32 v[28:29], v[28:29], v[64:65] op_sel_hi:[1,0]
	v_pk_mul_f32 v[30:31], v[30:31], v[64:65] op_sel_hi:[1,0]
	v_pk_mul_f32 v[8:9], v[8:9], v[64:65] op_sel_hi:[1,0]
	v_pk_mul_f32 v[10:11], v[10:11], v[64:65] op_sel_hi:[1,0]
	v_pk_mul_f32 v[12:13], v[12:13], v[64:65] op_sel_hi:[1,0]
	v_pk_mul_f32 v[14:15], v[14:15], v[64:65] op_sel_hi:[1,0]
	v_cvt_pk_bf16_f32 v56, v56, v57
	v_cvt_pk_bf16_f32 v57, v58, v59
	v_cvt_pk_bf16_f32 v58, v60, v61
	v_cvt_pk_bf16_f32 v59, v62, v63
	v_cvt_pk_bf16_f32 v40, v40, v41
	v_cvt_pk_bf16_f32 v41, v42, v43
	v_cvt_pk_bf16_f32 v42, v44, v45
	v_cvt_pk_bf16_f32 v43, v46, v47
	v_cvt_pk_bf16_f32 v24, v24, v25
	v_cvt_pk_bf16_f32 v25, v26, v27
	v_cvt_pk_bf16_f32 v26, v28, v29
	v_cvt_pk_bf16_f32 v27, v30, v31
	v_cvt_pk_bf16_f32 v8, v8, v9
	v_cvt_pk_bf16_f32 v9, v10, v11
	v_cvt_pk_bf16_f32 v10, v12, v13
	v_cvt_pk_bf16_f32 v11, v14, v15
	v_permlane32_swap_b32_e32 v56, v58
	v_permlane32_swap_b32_e32 v57, v59
	v_permlane32_swap_b32_e32 v40, v42
	v_permlane32_swap_b32_e32 v41, v43
	v_permlane32_swap_b32_e32 v24, v26
	v_permlane32_swap_b32_e32 v25, v27
	v_permlane32_swap_b32_e32 v8, v10
	v_permlane32_swap_b32_e32 v9, v11
	global_store_dwordx4 v[66:67], v[56:59], off offset:32
	global_store_dwordx4 v[66:67], v[40:43], off offset:96
	global_store_dwordx4 v[66:67], v[24:27], off offset:160
	global_store_dwordx4 v[66:67], v[8:11], off offset:224
	s_cmp_lg_u32 s59, s3
	s_mov_b32 s17, s59
	s_cbranch_scc0 .LBB0_1538
